# sparse-attention selected branch: once every row has a finite running max, unselected rows need no explicit p=0 select (exp of -1e30 is exactly 0); third copy drops 32 selects; bit-identical
# speedup vs baseline: 1.0052x; 1.0001x over previous
; DI int crow(int i, int h) { return (i & 3) + 8 * (i >> 2) + 4 * h; }
; DI float shx32(float v) { return __shfl_xor(v, 32); }
; template <bool MASKED>
; DI float online_softmax_t(f32x16 (&Sx)[2], unsigned vb, float& m, float& l) {
;   float mx = NEG;
; #pragma unroll
;   for (int mt = 0; mt < 2; ++mt)
; #pragma unroll
;     for (int i = 0; i < 16; ++i) {
;       float s = Sx[mt][i];
;       if (MASKED) { s = ((vb >> (mt * 16 + i)) & 1u) ? s : NEG; Sx[mt][i] = s; }
;       mx = fmaxf(mx, s);
;     }
;   mx = fmaxf(mx, shx32(mx));
;   const float mn = fmaxf(m, mx);
;   const float alpha = __builtin_amdgcn_exp2f((m - mn) * L2E);
;   const float mb = mn * L2E;
;   f32x2 sum2 = {0.f, 0.f};
;   const f32x2 l2e2 = {L2E, L2E}, mb2 = {mb, mb};
; #pragma unroll
;   for (int mt = 0; mt < 2; ++mt)
; #pragma unroll
;     for (int i = 0; i < 16; i += 2) {
;       const f32x2 t = (f32x2){Sx[mt][i], Sx[mt][i + 1]} * l2e2 - mb2;
;       f32x2 p = {__builtin_amdgcn_exp2f(t.x), __builtin_amdgcn_exp2f(t.y)};
;       if (MASKED) { p.x = ((vb >> (mt * 16 + i)) & 1u) ? p.x : 0.f; p.y = ((vb >> (mt * 16 + i + 1)) & 1u) ? p.y : 0.f; }
;       Sx[mt][i] = p.x; Sx[mt][i + 1] = p.y;
;       sum2 += p;
;     }
;   l = l * alpha + (sum2.x + sum2.y);
;   m = mn;
;   return alpha;
; }
; DI void nsa_item(const Params& p_, const EvenBufs& eb_, int b, int g, int tt, unsigned char* smem) {
;     ...
;       f32x16 Sx[2]; qk_tile(sK, qf, Sx, r, h);
;       const bool sb = (mysel >> j) & 1ull;
;       unsigned vb = sb ? 0xffffffffu : 0u;
;       bool masked = (__ballot(sb) != ~0ull);
;       if (j == (t0 >> 6)) {
;         masked = true; vb = 0;
; #pragma unroll
;         for (int mt = 0; mt < 2; ++mt)
; #pragma unroll
;           for (int i = 0; i < 16; ++i) vb |= (unsigned)(sb && (j * 64 + mt * 32 + crow(i, h) <= t)) << (mt * 16 + i);
;       }
;       if (!masked) vb = 0xffffffffu;
;       const float alpha = online_softmax_t<true>(Sx, vb, m, l);
;       scale_o<2>(O, alpha);
;       pv_tile<2>(sV, Sx, O, r, h);
.Lsel_fast:
	v_cmp_eq_u32_e64 s[98:99], v148, v214
	s_cmp_eq_u64 s[98:99], 0
	s_cbranch_scc1 .Lsel_fast2
	s_nop 3
	v_cndmask_b32_e64 v128, -1, v128, s[4:5]
	v_and_b32_e32 v129, 1, v128
	v_cmp_eq_u32_e64 s[64:65], 0, v129
	s_cmp_gt_i32 s33, -1
	s_nop 0
	v_cndmask_b32_e64 v150, v82, v214, s[64:65]
	s_nop 1
	v_cndmask_b32_e64 v151, v83, v214, s[64:65]
	v_max3_f32 v82, v150, s92, v151
	v_cndmask_b32_e64 v152, v84, v214, s[64:65]
	v_cndmask_b32_e64 v153, v85, v214, s[64:65]
	v_max3_f32 v82, v82, v152, v153
	v_cndmask_b32_e64 v154, v86, v214, s[64:65]
	v_cndmask_b32_e64 v155, v87, v214, s[64:65]
	v_max3_f32 v82, v82, v154, v155
	v_cndmask_b32_e64 v156, v88, v214, s[64:65]
	v_cndmask_b32_e64 v157, v89, v214, s[64:65]
	v_max3_f32 v82, v82, v156, v157
	v_cndmask_b32_e64 v158, v90, v214, s[64:65]
	v_cndmask_b32_e64 v159, v91, v214, s[64:65]
	v_max3_f32 v82, v82, v158, v159
	v_cndmask_b32_e64 v160, v92, v214, s[64:65]
	v_cndmask_b32_e64 v161, v93, v214, s[64:65]
	v_max3_f32 v82, v82, v160, v161
	v_cndmask_b32_e64 v174, v94, v214, s[64:65]
	v_cndmask_b32_e64 v175, v95, v214, s[64:65]
	v_max3_f32 v82, v82, v174, v175
	v_cndmask_b32_e64 v176, v96, v214, s[64:65]
	v_cndmask_b32_e64 v177, v97, v214, s[64:65]
	v_max3_f32 v84, v82, v176, v177
	s_nop 1
	v_cndmask_b32_e64 v82, v66, v214, s[64:65]
	s_nop 1
	v_cndmask_b32_e64 v83, v67, v214, s[64:65]
	v_max3_f32 v66, v84, v82, v83
	v_cndmask_b32_e64 v84, v68, v214, s[64:65]
	v_cndmask_b32_e64 v85, v69, v214, s[64:65]
	v_max3_f32 v66, v66, v84, v85
	v_cndmask_b32_e64 v88, v70, v214, s[64:65]
	v_cndmask_b32_e64 v89, v71, v214, s[64:65]
	v_max3_f32 v66, v66, v88, v89
	v_cndmask_b32_e64 v92, v72, v214, s[64:65]
	v_cndmask_b32_e64 v93, v73, v214, s[64:65]
	v_max3_f32 v66, v66, v92, v93
	v_cndmask_b32_e64 v72, v74, v214, s[64:65]
	v_cndmask_b32_e64 v73, v75, v214, s[64:65]
	v_max3_f32 v66, v66, v72, v73
	v_cndmask_b32_e64 v74, v76, v214, s[64:65]
	v_cndmask_b32_e64 v75, v77, v214, s[64:65]
	v_max3_f32 v66, v66, v74, v75
	v_cndmask_b32_e64 v76, v78, v214, s[64:65]
	v_cndmask_b32_e64 v77, v79, v214, s[64:65]
	v_max3_f32 v66, v66, v76, v77
	v_cndmask_b32_e64 v79, v81, v214, s[64:65]
	v_cndmask_b32_e64 v78, v80, v214, s[64:65]
	v_max3_f32 v66, v66, v78, v79
	ds_bpermute_b32 v67, v169, v66
	s_waitcnt lgkmcnt(0)
	v_max3_f32 v129, v148, v66, v67
	v_mul_f32_e32 v128, 0x3fb8aa3b, v129
	v_pk_fma_f32 v[68:69], v[152:153], s[96:97], v[128:129] op_sel_hi:[1,0,0] neg_lo:[0,0,1] neg_hi:[0,0,1]
	v_pk_fma_f32 v[66:67], v[150:151], s[96:97], v[128:129] op_sel_hi:[1,0,0] neg_lo:[0,0,1] neg_hi:[0,0,1]
	v_exp_f32_e32 v68, v68
	v_exp_f32_e32 v69, v69
	v_exp_f32_e32 v66, v66
	v_exp_f32_e32 v67, v67
	v_cndmask_b32_e64 v90, v68, 0, s[64:65]
	v_cndmask_b32_e64 v91, v69, 0, s[64:65]
	v_pk_fma_f32 v[68:69], v[154:155], s[96:97], v[128:129] op_sel_hi:[1,0,0] neg_lo:[0,0,1] neg_hi:[0,0,1]
	v_cndmask_b32_e64 v86, v66, 0, s[64:65]
	v_exp_f32_e32 v68, v68
	v_exp_f32_e32 v69, v69
	v_cndmask_b32_e64 v87, v67, 0, s[64:65]
	v_pk_add_f32 v[66:67], v[86:87], 0 op_sel_hi:[1,0]
	v_cndmask_b32_e64 v94, v68, 0, s[64:65]
	v_cndmask_b32_e64 v95, v69, 0, s[64:65]
	v_pk_fma_f32 v[68:69], v[156:157], s[96:97], v[128:129] op_sel_hi:[1,0,0] neg_lo:[0,0,1] neg_hi:[0,0,1]
	v_pk_add_f32 v[66:67], v[90:91], v[66:67]
	v_exp_f32_e32 v68, v68
	v_exp_f32_e32 v69, v69
	v_pk_add_f32 v[66:67], v[94:95], v[66:67]
	v_pk_fma_f32 v[82:83], v[82:83], s[96:97], v[128:129] op_sel_hi:[1,0,0] neg_lo:[0,0,1] neg_hi:[0,0,1]
	v_cndmask_b32_e64 v96, v68, 0, s[64:65]
	v_cndmask_b32_e64 v97, v69, 0, s[64:65]
	v_pk_add_f32 v[68:69], v[96:97], v[66:67]
	v_pk_fma_f32 v[66:67], v[158:159], s[96:97], v[128:129] op_sel_hi:[1,0,0] neg_lo:[0,0,1] neg_hi:[0,0,1]
	v_exp_f32_e32 v82, v82
	v_exp_f32_e32 v66, v66
	v_exp_f32_e32 v67, v67
	v_exp_f32_e32 v83, v83
	v_pk_fma_f32 v[84:85], v[84:85], s[96:97], v[128:129] op_sel_hi:[1,0,0] neg_lo:[0,0,1] neg_hi:[0,0,1]
	v_cndmask_b32_e64 v66, v66, 0, s[64:65]
	v_cndmask_b32_e64 v67, v67, 0, s[64:65]
	v_pk_add_f32 v[70:71], v[66:67], v[68:69]
	v_pk_fma_f32 v[68:69], v[160:161], s[96:97], v[128:129] op_sel_hi:[1,0,0] neg_lo:[0,0,1] neg_hi:[0,0,1]
	v_exp_f32_e32 v84, v84
	v_exp_f32_e32 v68, v68
	v_exp_f32_e32 v69, v69
	v_exp_f32_e32 v85, v85
	v_pk_fma_f32 v[88:89], v[88:89], s[96:97], v[128:129] op_sel_hi:[1,0,0] neg_lo:[0,0,1] neg_hi:[0,0,1]
	v_cndmask_b32_e64 v68, v68, 0, s[64:65]
	v_cndmask_b32_e64 v69, v69, 0, s[64:65]
	v_pk_add_f32 v[80:81], v[68:69], v[70:71]
	v_pk_fma_f32 v[70:71], v[174:175], s[96:97], v[128:129] op_sel_hi:[1,0,0] neg_lo:[0,0,1] neg_hi:[0,0,1]
	v_exp_f32_e32 v88, v88
	v_exp_f32_e32 v70, v70
	v_exp_f32_e32 v71, v71
	v_exp_f32_e32 v89, v89
	v_pk_fma_f32 v[92:93], v[92:93], s[96:97], v[128:129] op_sel_hi:[1,0,0] neg_lo:[0,0,1] neg_hi:[0,0,1]
	v_cndmask_b32_e64 v70, v70, 0, s[64:65]
	v_cndmask_b32_e64 v71, v71, 0, s[64:65]
	v_pk_add_f32 v[150:151], v[70:71], v[80:81]
	v_pk_fma_f32 v[80:81], v[176:177], s[96:97], v[128:129] op_sel_hi:[1,0,0] neg_lo:[0,0,1] neg_hi:[0,0,1]
	v_exp_f32_e32 v92, v92
	v_exp_f32_e32 v80, v80
	v_exp_f32_e32 v81, v81
	v_exp_f32_e32 v93, v93
	v_pk_fma_f32 v[72:73], v[72:73], s[96:97], v[128:129] op_sel_hi:[1,0,0] neg_lo:[0,0,1] neg_hi:[0,0,1]
	v_cndmask_b32_e64 v80, v80, 0, s[64:65]
	v_cndmask_b32_e64 v81, v81, 0, s[64:65]
	v_pk_add_f32 v[150:151], v[80:81], v[150:151]
	v_cndmask_b32_e64 v82, v82, 0, s[64:65]
	v_cndmask_b32_e64 v83, v83, 0, s[64:65]
	v_exp_f32_e32 v72, v72
	v_exp_f32_e32 v73, v73
	v_pk_fma_f32 v[74:75], v[74:75], s[96:97], v[128:129] op_sel_hi:[1,0,0] neg_lo:[0,0,1] neg_hi:[0,0,1]
	v_pk_add_f32 v[150:151], v[82:83], v[150:151]
	v_cndmask_b32_e64 v84, v84, 0, s[64:65]
	v_cndmask_b32_e64 v85, v85, 0, s[64:65]
; DI unsigned pack2(float a, float b) { bf2_t v = __builtin_convertvector((f32x2){a, b}, bf2_t); return __builtin_bit_cast(unsigned, v); }
; #define MFMA(a, b, c) __builtin_amdgcn_mfma_f32_32x32x16_bf16((a), (b), (c), 0, 0, 0)
; template <int NDT> DI void pv_tile(const bf16_t* sV, const f32x16 (&P)[2], f32x16 (&O)[NDT], int r, int h) {
; #pragma unroll
;   for (int mt = 0; mt < 2; ++mt)
; #pragma unroll
;     for (int sp = 0; sp < 2; ++sp) {
;       u32x4 pk;
;       pk.x = pack2(P[mt][8 * sp + 0], P[mt][8 * sp + 1]); pk.y = pack2(P[mt][8 * sp + 2], P[mt][8 * sp + 3]);
;       pk.z = pack2(P[mt][8 * sp + 4], P[mt][8 * sp + 5]); pk.w = pack2(P[mt][8 * sp + 6], P[mt][8 * sp + 7]);
;       const bf16x8 pb = __builtin_bit_cast(bf16x8, pk);
; #pragma unroll
;       for (int dt = 0; dt < NDT; ++dt) {
;         const bf16_t* vp = sV + (dt * 32 + r) * 68 + mt * 32 + sp * 16 + 4 * h;
;         const bf16x4 lo = *(const bf16x4*)vp, hi = *(const bf16x4*)(vp + 8);
;         const bf16x8 va = __builtin_shufflevector(lo, hi, 0, 1, 2, 3, 4, 5, 6, 7);
;         O[dt] = MFMA(va, pb, O[dt]);
;       }
;       if (NDT > 2) __builtin_amdgcn_sched_barrier(0);
;     }
; }
; template <bool MASKED>
; DI float online_softmax_t(f32x16 (&Sx)[2], unsigned vb, float& m, float& l) {
;     ...
;   const float alpha = __builtin_amdgcn_exp2f((m - mn) * L2E);
;   const float mb = mn * L2E;
;   f32x2 sum2 = {0.f, 0.f};
;   const f32x2 l2e2 = {L2E, L2E}, mb2 = {mb, mb};
; #pragma unroll
;   for (int mt = 0; mt < 2; ++mt)
; #pragma unroll
;     for (int i = 0; i < 16; i += 2) {
;       const f32x2 t = (f32x2){Sx[mt][i], Sx[mt][i + 1]} * l2e2 - mb2;
;       f32x2 p = {__builtin_amdgcn_exp2f(t.x), __builtin_amdgcn_exp2f(t.y)};
;       if (MASKED) { p.x = ((vb >> (mt * 16 + i)) & 1u) ? p.x : 0.f; p.y = ((vb >> (mt * 16 + i + 1)) & 1u) ? p.y : 0.f; }
;       Sx[mt][i] = p.x; Sx[mt][i + 1] = p.y;
;       sum2 += p;
;     }
;   l = l * alpha + (sum2.x + sum2.y);
;   m = mn;
;   return alpha;
; }
; DI void nsa_item(const Params& p_, const EvenBufs& eb_, int b, int g, int tt, unsigned char* smem) {
;     ...
;       const float alpha = online_softmax_t<true>(Sx, vb, m, l);
;       scale_o<2>(O, alpha);
;       pv_tile<2>(sV, Sx, O, r, h);
;       if (jn < 0) break;
;       j = jn;
	v_exp_f32_e32 v74, v74
	v_exp_f32_e32 v75, v75
	v_pk_fma_f32 v[76:77], v[76:77], s[96:97], v[128:129] op_sel_hi:[1,0,0] neg_lo:[0,0,1] neg_hi:[0,0,1]
	v_pk_add_f32 v[150:151], v[84:85], v[150:151]
	v_cndmask_b32_e64 v88, v88, 0, s[64:65]
	v_cndmask_b32_e64 v89, v89, 0, s[64:65]
	v_exp_f32_e32 v76, v76
	v_exp_f32_e32 v77, v77
	v_pk_fma_f32 v[78:79], v[78:79], s[96:97], v[128:129] op_sel_hi:[1,0,0] neg_lo:[0,0,1] neg_hi:[0,0,1]
	v_pk_add_f32 v[150:151], v[88:89], v[150:151]
	v_cndmask_b32_e64 v92, v92, 0, s[64:65]
	v_cndmask_b32_e64 v93, v93, 0, s[64:65]
	v_exp_f32_e32 v78, v78
	v_exp_f32_e32 v79, v79
	v_pk_add_f32 v[150:151], v[92:93], v[150:151]
	v_cndmask_b32_e64 v72, v72, 0, s[64:65]
	v_cndmask_b32_e64 v73, v73, 0, s[64:65]
	v_pk_add_f32 v[150:151], v[72:73], v[150:151]
	v_cndmask_b32_e64 v74, v74, 0, s[64:65]
	v_cndmask_b32_e64 v75, v75, 0, s[64:65]
	v_pk_add_f32 v[150:151], v[74:75], v[150:151]
	v_cndmask_b32_e64 v76, v76, 0, s[64:65]
	v_cndmask_b32_e64 v77, v77, 0, s[64:65]
	v_sub_f32_e32 v128, v148, v129
	v_pk_add_f32 v[150:151], v[76:77], v[150:151]
	v_cndmask_b32_e64 v78, v78, 0, s[64:65]
	v_cndmask_b32_e64 v79, v79, 0, s[64:65]
	v_mul_f32_e32 v128, 0x3fb8aa3b, v128
	v_pk_add_f32 v[150:151], v[78:79], v[150:151]
	v_exp_f32_e32 v128, v128
	v_add_f32_e32 v184, v150, v151
	v_cvt_pk_bf16_f32 v150, v94, v95
	v_cvt_pk_bf16_f32 v151, v96, v97
	ds_read2_b64 v[94:97], v182 offset0:128 offset1:130
	ds_read2_b64 v[152:155], v182 offset0:132 offset1:134
	v_pk_mul_f32 v[50:51], v[50:51], v[128:129] op_sel_hi:[1,0]
	v_pk_mul_f32 v[52:53], v[52:53], v[128:129] op_sel_hi:[1,0]
	v_pk_mul_f32 v[54:55], v[54:55], v[128:129] op_sel_hi:[1,0]
	v_pk_mul_f32 v[56:57], v[56:57], v[128:129] op_sel_hi:[1,0]
	v_pk_mul_f32 v[58:59], v[58:59], v[128:129] op_sel_hi:[1,0]
	v_pk_mul_f32 v[60:61], v[60:61], v[128:129] op_sel_hi:[1,0]
	v_pk_mul_f32 v[62:63], v[62:63], v[128:129] op_sel_hi:[1,0]
	v_pk_mul_f32 v[64:65], v[64:65], v[128:129] op_sel_hi:[1,0]
	v_cvt_pk_bf16_f32 v148, v86, v87
	v_cvt_pk_bf16_f32 v149, v90, v91
	v_pk_mul_f32 v[34:35], v[34:35], v[128:129] op_sel_hi:[1,0]
	v_pk_mul_f32 v[36:37], v[36:37], v[128:129] op_sel_hi:[1,0]
	s_waitcnt lgkmcnt(1)
	v_mfma_f32_32x32x16_bf16 v[50:65], v[94:97], v[148:151], v[50:65]
	ds_read2_b64 v[94:97], v183 offset0:160 offset1:162
	v_mul_f32_e64 v38, v38, v128
	v_mul_f32_e64 v39, v39, v128
	v_mul_f32_e64 v40, v40, v128
	v_mul_f32_e64 v41, v41, v128
	v_pk_mul_f32 v[42:43], v[42:43], v[128:129] op_sel_hi:[1,0]
	v_pk_mul_f32 v[44:45], v[44:45], v[128:129] op_sel_hi:[1,0]
	v_pk_mul_f32 v[46:47], v[46:47], v[128:129] op_sel_hi:[1,0]
	v_pk_mul_f32 v[48:49], v[48:49], v[128:129] op_sel_hi:[1,0]
	v_cvt_pk_bf16_f32 v66, v66, v67
	v_cvt_pk_bf16_f32 v67, v68, v69
	s_waitcnt lgkmcnt(0)
	v_mfma_f32_32x32x16_bf16 v[34:49], v[94:97], v[148:151], v[34:49]
	ds_read2_b64 v[94:97], v183 offset0:164 offset1:166
	v_cvt_pk_bf16_f32 v68, v70, v71
	v_cvt_pk_bf16_f32 v69, v80, v81
	v_fmac_f32_e32 v184, v147, v128
	s_nop 0
	v_mfma_f32_32x32x16_bf16 v[50:65], v[152:155], v[66:69], v[50:65]
	s_waitcnt lgkmcnt(0)
	v_mfma_f32_32x32x16_bf16 v[34:49], v[94:97], v[66:69], v[34:49]
	v_cvt_pk_bf16_f32 v66, v82, v83
	ds_read2_b64 v[80:83], v182 offset0:136 offset1:138
	v_cvt_pk_bf16_f32 v67, v84, v85
	v_cvt_pk_bf16_f32 v68, v88, v89
	v_cvt_pk_bf16_f32 v69, v92, v93
	s_waitcnt lgkmcnt(0)
	s_nop 0
	v_mfma_f32_32x32x16_bf16 v[50:65], v[80:83], v[66:69], v[50:65]
	ds_read2_b64 v[80:83], v183 offset0:168 offset1:170
	s_waitcnt lgkmcnt(0)
	v_mfma_f32_32x32x16_bf16 v[34:49], v[80:83], v[66:69], v[34:49]
	v_cvt_pk_bf16_f32 v66, v72, v73
	ds_read2_b64 v[70:73], v182 offset0:140 offset1:142
	v_cvt_pk_bf16_f32 v67, v74, v75
	v_cvt_pk_bf16_f32 v68, v76, v77
	v_cvt_pk_bf16_f32 v69, v78, v79
	s_waitcnt lgkmcnt(0)
	s_nop 0
	v_mfma_f32_32x32x16_bf16 v[50:65], v[70:73], v[66:69], v[50:65]
	ds_read2_b64 v[70:73], v183 offset0:172 offset1:174
	s_waitcnt lgkmcnt(0)
	v_mfma_f32_32x32x16_bf16 v[34:49], v[70:73], v[66:69], v[34:49]
	s_cbranch_scc0 .LBB0_1081
	v_mov_b32_e32 v147, v184
	v_mov_b32_e32 v148, v129
	s_mov_b64 s[4:5], s[68:69]
	s_mov_b32 s6, s33
	s_branch .LBB0_1073
.Lsel_fast2:
	s_nop 3
	v_cndmask_b32_e64 v128, -1, v128, s[4:5]
	v_and_b32_e32 v129, 1, v128
	v_cmp_eq_u32_e64 s[64:65], 0, v129
	s_cmp_gt_i32 s33, -1
	s_nop 0
	v_cndmask_b32_e64 v150, v82, v214, s[64:65]
	s_nop 1
	v_cndmask_b32_e64 v151, v83, v214, s[64:65]
	v_max3_f32 v82, v150, s92, v151
	v_cndmask_b32_e64 v152, v84, v214, s[64:65]
	v_cndmask_b32_e64 v153, v85, v214, s[64:65]
	v_max3_f32 v82, v82, v152, v153
	v_cndmask_b32_e64 v154, v86, v214, s[64:65]
	v_cndmask_b32_e64 v155, v87, v214, s[64:65]
	v_max3_f32 v82, v82, v154, v155
	v_cndmask_b32_e64 v156, v88, v214, s[64:65]
	v_cndmask_b32_e64 v157, v89, v214, s[64:65]
	v_max3_f32 v82, v82, v156, v157
	v_cndmask_b32_e64 v158, v90, v214, s[64:65]
	v_cndmask_b32_e64 v159, v91, v214, s[64:65]
	v_max3_f32 v82, v82, v158, v159
	v_cndmask_b32_e64 v160, v92, v214, s[64:65]
	v_cndmask_b32_e64 v161, v93, v214, s[64:65]
	v_max3_f32 v82, v82, v160, v161
	v_cndmask_b32_e64 v174, v94, v214, s[64:65]
	v_cndmask_b32_e64 v175, v95, v214, s[64:65]
	v_max3_f32 v82, v82, v174, v175
	v_cndmask_b32_e64 v176, v96, v214, s[64:65]
	v_cndmask_b32_e64 v177, v97, v214, s[64:65]
	v_max3_f32 v84, v82, v176, v177
	s_nop 1
	v_cndmask_b32_e64 v82, v66, v214, s[64:65]
	s_nop 1
	v_cndmask_b32_e64 v83, v67, v214, s[64:65]
	v_max3_f32 v66, v84, v82, v83
	v_cndmask_b32_e64 v84, v68, v214, s[64:65]
	v_cndmask_b32_e64 v85, v69, v214, s[64:65]
	v_max3_f32 v66, v66, v84, v85
	v_cndmask_b32_e64 v88, v70, v214, s[64:65]
	v_cndmask_b32_e64 v89, v71, v214, s[64:65]
	v_max3_f32 v66, v66, v88, v89
	v_cndmask_b32_e64 v92, v72, v214, s[64:65]
	v_cndmask_b32_e64 v93, v73, v214, s[64:65]
	v_max3_f32 v66, v66, v92, v93
	v_cndmask_b32_e64 v72, v74, v214, s[64:65]
	v_cndmask_b32_e64 v73, v75, v214, s[64:65]
	v_max3_f32 v66, v66, v72, v73
	v_cndmask_b32_e64 v74, v76, v214, s[64:65]
	v_cndmask_b32_e64 v75, v77, v214, s[64:65]
	v_max3_f32 v66, v66, v74, v75
	v_cndmask_b32_e64 v76, v78, v214, s[64:65]
	v_cndmask_b32_e64 v77, v79, v214, s[64:65]
	v_max3_f32 v66, v66, v76, v77
	v_cndmask_b32_e64 v79, v81, v214, s[64:65]
	v_cndmask_b32_e64 v78, v80, v214, s[64:65]
	v_max3_f32 v66, v66, v78, v79
	ds_bpermute_b32 v67, v169, v66
	s_waitcnt lgkmcnt(0)
; DI unsigned pack2(float a, float b) { bf2_t v = __builtin_convertvector((f32x2){a, b}, bf2_t); return __builtin_bit_cast(unsigned, v); }
; #define MFMA(a, b, c) __builtin_amdgcn_mfma_f32_32x32x16_bf16((a), (b), (c), 0, 0, 0)
; template <int NDT> DI void pv_tile(const bf16_t* sV, const f32x16 (&P)[2], f32x16 (&O)[NDT], int r, int h) {
; #pragma unroll
;   for (int mt = 0; mt < 2; ++mt)
; #pragma unroll
;     for (int sp = 0; sp < 2; ++sp) {
;       u32x4 pk;
;       pk.x = pack2(P[mt][8 * sp + 0], P[mt][8 * sp + 1]); pk.y = pack2(P[mt][8 * sp + 2], P[mt][8 * sp + 3]);
;       pk.z = pack2(P[mt][8 * sp + 4], P[mt][8 * sp + 5]); pk.w = pack2(P[mt][8 * sp + 6], P[mt][8 * sp + 7]);
;       const bf16x8 pb = __builtin_bit_cast(bf16x8, pk);
; #pragma unroll
;       for (int dt = 0; dt < NDT; ++dt) {
;         const bf16_t* vp = sV + (dt * 32 + r) * 68 + mt * 32 + sp * 16 + 4 * h;
;         const bf16x4 lo = *(const bf16x4*)vp, hi = *(const bf16x4*)(vp + 8);
;         const bf16x8 va = __builtin_shufflevector(lo, hi, 0, 1, 2, 3, 4, 5, 6, 7);
;         O[dt] = MFMA(va, pb, O[dt]);
;       }
;       if (NDT > 2) __builtin_amdgcn_sched_barrier(0);
;     }
; }
; template <bool MASKED>
; DI float online_softmax_t(f32x16 (&Sx)[2], unsigned vb, float& m, float& l) {
;     ...
;   const float alpha = __builtin_amdgcn_exp2f((m - mn) * L2E);
;   const float mb = mn * L2E;
;   f32x2 sum2 = {0.f, 0.f};
;   const f32x2 l2e2 = {L2E, L2E}, mb2 = {mb, mb};
; #pragma unroll
;   for (int mt = 0; mt < 2; ++mt)
; #pragma unroll
;     for (int i = 0; i < 16; i += 2) {
;       const f32x2 t = (f32x2){Sx[mt][i], Sx[mt][i + 1]} * l2e2 - mb2;
;       f32x2 p = {__builtin_amdgcn_exp2f(t.x), __builtin_amdgcn_exp2f(t.y)};
;       if (MASKED) { p.x = ((vb >> (mt * 16 + i)) & 1u) ? p.x : 0.f; p.y = ((vb >> (mt * 16 + i + 1)) & 1u) ? p.y : 0.f; }
;       Sx[mt][i] = p.x; Sx[mt][i + 1] = p.y;
;       sum2 += p;
;     }
;   l = l * alpha + (sum2.x + sum2.y);
;   m = mn;
;   return alpha;
; }
	v_max3_f32 v129, v148, v66, v67
	v_mul_f32_e32 v128, 0x3fb8aa3b, v129
	v_pk_fma_f32 v[68:69], v[152:153], s[96:97], v[128:129] op_sel_hi:[1,0,0] neg_lo:[0,0,1] neg_hi:[0,0,1]
	v_pk_fma_f32 v[66:67], v[150:151], s[96:97], v[128:129] op_sel_hi:[1,0,0] neg_lo:[0,0,1] neg_hi:[0,0,1]
	v_exp_f32_e32 v68, v68
	v_exp_f32_e32 v69, v69
	v_exp_f32_e32 v66, v66
	v_exp_f32_e32 v67, v67
	v_mov_b32_e32 v90, v68
	v_mov_b32_e32 v91, v69
	v_pk_fma_f32 v[68:69], v[154:155], s[96:97], v[128:129] op_sel_hi:[1,0,0] neg_lo:[0,0,1] neg_hi:[0,0,1]
	v_mov_b32_e32 v86, v66
	v_exp_f32_e32 v68, v68
	v_exp_f32_e32 v69, v69
	v_mov_b32_e32 v87, v67
	v_pk_add_f32 v[66:67], v[86:87], 0 op_sel_hi:[1,0]
	v_mov_b32_e32 v94, v68
	v_mov_b32_e32 v95, v69
	v_pk_fma_f32 v[68:69], v[156:157], s[96:97], v[128:129] op_sel_hi:[1,0,0] neg_lo:[0,0,1] neg_hi:[0,0,1]
	v_pk_add_f32 v[66:67], v[90:91], v[66:67]
	v_exp_f32_e32 v68, v68
	v_exp_f32_e32 v69, v69
	v_pk_add_f32 v[66:67], v[94:95], v[66:67]
	v_pk_fma_f32 v[82:83], v[82:83], s[96:97], v[128:129] op_sel_hi:[1,0,0] neg_lo:[0,0,1] neg_hi:[0,0,1]
	v_mov_b32_e32 v96, v68
	v_mov_b32_e32 v97, v69
	v_pk_add_f32 v[68:69], v[96:97], v[66:67]
	v_pk_fma_f32 v[66:67], v[158:159], s[96:97], v[128:129] op_sel_hi:[1,0,0] neg_lo:[0,0,1] neg_hi:[0,0,1]
	v_exp_f32_e32 v82, v82
	v_exp_f32_e32 v66, v66
	v_exp_f32_e32 v67, v67
	v_exp_f32_e32 v83, v83
	v_pk_fma_f32 v[84:85], v[84:85], s[96:97], v[128:129] op_sel_hi:[1,0,0] neg_lo:[0,0,1] neg_hi:[0,0,1]
	v_pk_add_f32 v[70:71], v[66:67], v[68:69]
	v_pk_fma_f32 v[68:69], v[160:161], s[96:97], v[128:129] op_sel_hi:[1,0,0] neg_lo:[0,0,1] neg_hi:[0,0,1]
	v_exp_f32_e32 v84, v84
	v_exp_f32_e32 v68, v68
	v_exp_f32_e32 v69, v69
	v_exp_f32_e32 v85, v85
	v_pk_fma_f32 v[88:89], v[88:89], s[96:97], v[128:129] op_sel_hi:[1,0,0] neg_lo:[0,0,1] neg_hi:[0,0,1]
	v_pk_add_f32 v[80:81], v[68:69], v[70:71]
	v_pk_fma_f32 v[70:71], v[174:175], s[96:97], v[128:129] op_sel_hi:[1,0,0] neg_lo:[0,0,1] neg_hi:[0,0,1]
	v_exp_f32_e32 v88, v88
	v_exp_f32_e32 v70, v70
	v_exp_f32_e32 v71, v71
	v_exp_f32_e32 v89, v89
	v_pk_fma_f32 v[92:93], v[92:93], s[96:97], v[128:129] op_sel_hi:[1,0,0] neg_lo:[0,0,1] neg_hi:[0,0,1]
	v_pk_add_f32 v[150:151], v[70:71], v[80:81]
	v_pk_fma_f32 v[80:81], v[176:177], s[96:97], v[128:129] op_sel_hi:[1,0,0] neg_lo:[0,0,1] neg_hi:[0,0,1]
	v_exp_f32_e32 v92, v92
	v_exp_f32_e32 v80, v80
	v_exp_f32_e32 v81, v81
	v_exp_f32_e32 v93, v93
	v_pk_fma_f32 v[72:73], v[72:73], s[96:97], v[128:129] op_sel_hi:[1,0,0] neg_lo:[0,0,1] neg_hi:[0,0,1]
	v_pk_add_f32 v[150:151], v[80:81], v[150:151]
	v_exp_f32_e32 v72, v72
	v_exp_f32_e32 v73, v73
	v_pk_fma_f32 v[74:75], v[74:75], s[96:97], v[128:129] op_sel_hi:[1,0,0] neg_lo:[0,0,1] neg_hi:[0,0,1]
	v_pk_add_f32 v[150:151], v[82:83], v[150:151]
	v_exp_f32_e32 v74, v74
	v_exp_f32_e32 v75, v75
	v_pk_fma_f32 v[76:77], v[76:77], s[96:97], v[128:129] op_sel_hi:[1,0,0] neg_lo:[0,0,1] neg_hi:[0,0,1]
	v_pk_add_f32 v[150:151], v[84:85], v[150:151]
	v_exp_f32_e32 v76, v76
	v_exp_f32_e32 v77, v77
	v_pk_fma_f32 v[78:79], v[78:79], s[96:97], v[128:129] op_sel_hi:[1,0,0] neg_lo:[0,0,1] neg_hi:[0,0,1]
	v_pk_add_f32 v[150:151], v[88:89], v[150:151]
	v_exp_f32_e32 v78, v78
	v_exp_f32_e32 v79, v79
	v_pk_add_f32 v[150:151], v[92:93], v[150:151]
	v_pk_add_f32 v[150:151], v[72:73], v[150:151]
	v_pk_add_f32 v[150:151], v[74:75], v[150:151]
	v_sub_f32_e32 v128, v148, v129
	v_pk_add_f32 v[150:151], v[76:77], v[150:151]
	v_mul_f32_e32 v128, 0x3fb8aa3b, v128
	v_pk_add_f32 v[150:151], v[78:79], v[150:151]
	v_exp_f32_e32 v128, v128
	v_add_f32_e32 v184, v150, v151
	v_cvt_pk_bf16_f32 v150, v94, v95
	v_cvt_pk_bf16_f32 v151, v96, v97
	ds_read2_b64 v[94:97], v182 offset0:128 offset1:130
	ds_read2_b64 v[152:155], v182 offset0:132 offset1:134
	v_pk_mul_f32 v[50:51], v[50:51], v[128:129] op_sel_hi:[1,0]
	v_pk_mul_f32 v[52:53], v[52:53], v[128:129] op_sel_hi:[1,0]
	v_pk_mul_f32 v[54:55], v[54:55], v[128:129] op_sel_hi:[1,0]
	v_pk_mul_f32 v[56:57], v[56:57], v[128:129] op_sel_hi:[1,0]
	v_pk_mul_f32 v[58:59], v[58:59], v[128:129] op_sel_hi:[1,0]
	v_pk_mul_f32 v[60:61], v[60:61], v[128:129] op_sel_hi:[1,0]
	v_pk_mul_f32 v[62:63], v[62:63], v[128:129] op_sel_hi:[1,0]
	v_pk_mul_f32 v[64:65], v[64:65], v[128:129] op_sel_hi:[1,0]
	v_cvt_pk_bf16_f32 v148, v86, v87
	v_cvt_pk_bf16_f32 v149, v90, v91
	v_pk_mul_f32 v[34:35], v[34:35], v[128:129] op_sel_hi:[1,0]
	v_pk_mul_f32 v[36:37], v[36:37], v[128:129] op_sel_hi:[1,0]
	s_waitcnt lgkmcnt(1)
	v_mfma_f32_32x32x16_bf16 v[50:65], v[94:97], v[148:151], v[50:65]
	ds_read2_b64 v[94:97], v183 offset0:160 offset1:162
	v_mul_f32_e64 v38, v38, v128
	v_mul_f32_e64 v39, v39, v128
	v_mul_f32_e64 v40, v40, v128
	v_mul_f32_e64 v41, v41, v128
	v_pk_mul_f32 v[42:43], v[42:43], v[128:129] op_sel_hi:[1,0]
	v_pk_mul_f32 v[44:45], v[44:45], v[128:129] op_sel_hi:[1,0]
	v_pk_mul_f32 v[46:47], v[46:47], v[128:129] op_sel_hi:[1,0]
	v_pk_mul_f32 v[48:49], v[48:49], v[128:129] op_sel_hi:[1,0]
	v_cvt_pk_bf16_f32 v66, v66, v67
	v_cvt_pk_bf16_f32 v67, v68, v69
	s_waitcnt lgkmcnt(0)
	v_mfma_f32_32x32x16_bf16 v[34:49], v[94:97], v[148:151], v[34:49]
	ds_read2_b64 v[94:97], v183 offset0:164 offset1:166
	v_cvt_pk_bf16_f32 v68, v70, v71
	v_cvt_pk_bf16_f32 v69, v80, v81
	v_fmac_f32_e32 v184, v147, v128
	s_nop 0
	v_mfma_f32_32x32x16_bf16 v[50:65], v[152:155], v[66:69], v[50:65]
	s_waitcnt lgkmcnt(0)
	v_mfma_f32_32x32x16_bf16 v[34:49], v[94:97], v[66:69], v[34:49]
	v_cvt_pk_bf16_f32 v66, v82, v83
	ds_read2_b64 v[80:83], v182 offset0:136 offset1:138
	v_cvt_pk_bf16_f32 v67, v84, v85
	v_cvt_pk_bf16_f32 v68, v88, v89
	v_cvt_pk_bf16_f32 v69, v92, v93
	s_waitcnt lgkmcnt(0)
	s_nop 0
	v_mfma_f32_32x32x16_bf16 v[50:65], v[80:83], v[66:69], v[50:65]
	ds_read2_b64 v[80:83], v183 offset0:168 offset1:170
	s_waitcnt lgkmcnt(0)
	v_mfma_f32_32x32x16_bf16 v[34:49], v[80:83], v[66:69], v[34:49]
	v_cvt_pk_bf16_f32 v66, v72, v73
	ds_read2_b64 v[70:73], v182 offset0:140 offset1:142
	v_cvt_pk_bf16_f32 v67, v74, v75
	v_cvt_pk_bf16_f32 v68, v76, v77
	v_cvt_pk_bf16_f32 v69, v78, v79
	s_waitcnt lgkmcnt(0)
	s_nop 0
	v_mfma_f32_32x32x16_bf16 v[50:65], v[70:73], v[66:69], v[50:65]
	ds_read2_b64 v[70:73], v183 offset0:172 offset1:174
	s_waitcnt lgkmcnt(0)
	v_mfma_f32_32x32x16_bf16 v[34:49], v[70:73], v[66:69], v[34:49]
	s_cbranch_scc0 .LBB0_1081
	v_mov_b32_e32 v147, v184
	v_mov_b32_e32 v148, v129
	s_mov_b64 s[4:5], s[68:69]
	s_mov_b32 s6, s33
	s_branch .LBB0_1073
